# v74 + GEMM per-unit accumulator clears with 63 v_pk_mov_b32 instead of 127 v_mov_b32 (all ten GEMM phase instances)
# speedup vs baseline: 1.0123x; 1.0062x over previous
.LBB0_179:
	s_ashr_i32 s13, s12, 31
	s_lshl_b64 s[14:15], s[12:13], 19
	s_add_u32 s14, s76, s14
	s_addc_u32 s15, s77, s15
	s_and_b64 s[16:17], s[2:3], exec
	s_cselect_b32 s13, s15, s19
	s_cselect_b32 s41, s14, s18
	s_ashr_i32 s11, s10, 31
	s_lshl_b64 s[16:17], s[10:11], 19
	s_add_u32 s16, s24, s16
	s_addc_u32 s17, s25, s17
	s_and_b64 s[22:23], s[2:3], exec
	s_cselect_b32 s11, s17, s21
	s_cselect_b32 s42, s16, s20
	s_add_u32 s18, s18, 0x40080
	s_addc_u32 s19, s19, 0
	s_add_u32 s43, s20, 0x100
	v_mov_b32_e32 v0, 0
	s_addc_u32 s44, s21, 0
	s_mov_b32 s45, -2
	v_mov_b32_e32 v1, v0
	v_pk_mov_b32 v[2:3], v[0:1], v[0:1] op_sel:[0,0]
	v_pk_mov_b32 v[4:5], v[0:1], v[0:1] op_sel:[0,0]
	v_pk_mov_b32 v[6:7], v[0:1], v[0:1] op_sel:[0,0]
	v_pk_mov_b32 v[8:9], v[0:1], v[0:1] op_sel:[0,0]
	v_pk_mov_b32 v[10:11], v[0:1], v[0:1] op_sel:[0,0]
	v_pk_mov_b32 v[12:13], v[0:1], v[0:1] op_sel:[0,0]
	v_pk_mov_b32 v[14:15], v[0:1], v[0:1] op_sel:[0,0]
	v_pk_mov_b32 v[16:17], v[0:1], v[0:1] op_sel:[0,0]
	v_pk_mov_b32 v[18:19], v[0:1], v[0:1] op_sel:[0,0]
	v_pk_mov_b32 v[20:21], v[0:1], v[0:1] op_sel:[0,0]
	v_pk_mov_b32 v[22:23], v[0:1], v[0:1] op_sel:[0,0]
	v_pk_mov_b32 v[24:25], v[0:1], v[0:1] op_sel:[0,0]
	v_pk_mov_b32 v[26:27], v[0:1], v[0:1] op_sel:[0,0]
	v_pk_mov_b32 v[28:29], v[0:1], v[0:1] op_sel:[0,0]
	v_pk_mov_b32 v[30:31], v[0:1], v[0:1] op_sel:[0,0]
	v_pk_mov_b32 v[32:33], v[0:1], v[0:1] op_sel:[0,0]
	v_pk_mov_b32 v[34:35], v[0:1], v[0:1] op_sel:[0,0]
	v_pk_mov_b32 v[36:37], v[0:1], v[0:1] op_sel:[0,0]
	v_pk_mov_b32 v[38:39], v[0:1], v[0:1] op_sel:[0,0]
	v_pk_mov_b32 v[40:41], v[0:1], v[0:1] op_sel:[0,0]
	v_pk_mov_b32 v[42:43], v[0:1], v[0:1] op_sel:[0,0]
	v_pk_mov_b32 v[44:45], v[0:1], v[0:1] op_sel:[0,0]
	v_pk_mov_b32 v[46:47], v[0:1], v[0:1] op_sel:[0,0]
	v_pk_mov_b32 v[48:49], v[0:1], v[0:1] op_sel:[0,0]
	v_pk_mov_b32 v[50:51], v[0:1], v[0:1] op_sel:[0,0]
	v_pk_mov_b32 v[52:53], v[0:1], v[0:1] op_sel:[0,0]
	v_pk_mov_b32 v[54:55], v[0:1], v[0:1] op_sel:[0,0]
	v_pk_mov_b32 v[56:57], v[0:1], v[0:1] op_sel:[0,0]
	v_pk_mov_b32 v[58:59], v[0:1], v[0:1] op_sel:[0,0]
	v_pk_mov_b32 v[60:61], v[0:1], v[0:1] op_sel:[0,0]
	v_pk_mov_b32 v[62:63], v[0:1], v[0:1] op_sel:[0,0]
	v_pk_mov_b32 v[64:65], v[0:1], v[0:1] op_sel:[0,0]
	v_pk_mov_b32 v[66:67], v[0:1], v[0:1] op_sel:[0,0]
	v_pk_mov_b32 v[68:69], v[0:1], v[0:1] op_sel:[0,0]
	v_pk_mov_b32 v[70:71], v[0:1], v[0:1] op_sel:[0,0]
	v_pk_mov_b32 v[72:73], v[0:1], v[0:1] op_sel:[0,0]
	v_pk_mov_b32 v[74:75], v[0:1], v[0:1] op_sel:[0,0]
	v_pk_mov_b32 v[76:77], v[0:1], v[0:1] op_sel:[0,0]
	v_pk_mov_b32 v[78:79], v[0:1], v[0:1] op_sel:[0,0]
	v_pk_mov_b32 v[80:81], v[0:1], v[0:1] op_sel:[0,0]
	v_pk_mov_b32 v[82:83], v[0:1], v[0:1] op_sel:[0,0]
	v_pk_mov_b32 v[84:85], v[0:1], v[0:1] op_sel:[0,0]
	v_pk_mov_b32 v[86:87], v[0:1], v[0:1] op_sel:[0,0]
	v_pk_mov_b32 v[88:89], v[0:1], v[0:1] op_sel:[0,0]
	v_pk_mov_b32 v[90:91], v[0:1], v[0:1] op_sel:[0,0]
	v_pk_mov_b32 v[92:93], v[0:1], v[0:1] op_sel:[0,0]
	v_pk_mov_b32 v[94:95], v[0:1], v[0:1] op_sel:[0,0]
	v_pk_mov_b32 v[96:97], v[0:1], v[0:1] op_sel:[0,0]
	v_pk_mov_b32 v[98:99], v[0:1], v[0:1] op_sel:[0,0]
	v_pk_mov_b32 v[100:101], v[0:1], v[0:1] op_sel:[0,0]
	v_pk_mov_b32 v[102:103], v[0:1], v[0:1] op_sel:[0,0]
	v_pk_mov_b32 v[104:105], v[0:1], v[0:1] op_sel:[0,0]
	v_pk_mov_b32 v[106:107], v[0:1], v[0:1] op_sel:[0,0]
	v_pk_mov_b32 v[108:109], v[0:1], v[0:1] op_sel:[0,0]
	v_pk_mov_b32 v[110:111], v[0:1], v[0:1] op_sel:[0,0]
	v_pk_mov_b32 v[112:113], v[0:1], v[0:1] op_sel:[0,0]
	v_pk_mov_b32 v[114:115], v[0:1], v[0:1] op_sel:[0,0]
	v_pk_mov_b32 v[116:117], v[0:1], v[0:1] op_sel:[0,0]
	v_pk_mov_b32 v[118:119], v[0:1], v[0:1] op_sel:[0,0]
	v_pk_mov_b32 v[120:121], v[0:1], v[0:1] op_sel:[0,0]
	v_pk_mov_b32 v[122:123], v[0:1], v[0:1] op_sel:[0,0]
	v_pk_mov_b32 v[124:125], v[0:1], v[0:1] op_sel:[0,0]
	v_pk_mov_b32 v[126:127], v[0:1], v[0:1] op_sel:[0,0]

.LBB0_254:
	s_ashr_i32 s23, s22, 31
	s_lshl_b64 s[24:25], s[22:23], 19
	s_add_u32 s24, s76, s24
	s_addc_u32 s25, s77, s25
	s_and_b64 s[26:27], s[2:3], exec
	s_cselect_b32 s23, s25, s1
	s_cselect_b32 s54, s24, s0
	s_ashr_i32 s21, s20, 31
	s_lshl_b64 s[26:27], s[20:21], 19
	s_add_u32 s26, s36, s26
	s_addc_u32 s27, s37, s27
	s_and_b64 s[30:31], s[2:3], exec
	s_cselect_b32 s21, s27, s29
	s_cselect_b32 s55, s26, s28
	s_add_u32 s0, s0, 0x40080
	s_addc_u32 s1, s1, 0
	s_add_u32 s56, s28, 0x100
	v_mov_b32_e32 v0, 0
	s_addc_u32 s57, s29, 0
	s_mov_b32 s58, -2
	v_mov_b32_e32 v1, v0
	v_pk_mov_b32 v[2:3], v[0:1], v[0:1] op_sel:[0,0]
	v_pk_mov_b32 v[4:5], v[0:1], v[0:1] op_sel:[0,0]
	v_pk_mov_b32 v[6:7], v[0:1], v[0:1] op_sel:[0,0]
	v_pk_mov_b32 v[8:9], v[0:1], v[0:1] op_sel:[0,0]
	v_pk_mov_b32 v[10:11], v[0:1], v[0:1] op_sel:[0,0]
	v_pk_mov_b32 v[12:13], v[0:1], v[0:1] op_sel:[0,0]
	v_pk_mov_b32 v[14:15], v[0:1], v[0:1] op_sel:[0,0]
	v_pk_mov_b32 v[16:17], v[0:1], v[0:1] op_sel:[0,0]
	v_pk_mov_b32 v[18:19], v[0:1], v[0:1] op_sel:[0,0]
	v_pk_mov_b32 v[20:21], v[0:1], v[0:1] op_sel:[0,0]
	v_pk_mov_b32 v[22:23], v[0:1], v[0:1] op_sel:[0,0]
	v_pk_mov_b32 v[24:25], v[0:1], v[0:1] op_sel:[0,0]
	v_pk_mov_b32 v[26:27], v[0:1], v[0:1] op_sel:[0,0]
	v_pk_mov_b32 v[28:29], v[0:1], v[0:1] op_sel:[0,0]
	v_pk_mov_b32 v[30:31], v[0:1], v[0:1] op_sel:[0,0]
	v_pk_mov_b32 v[32:33], v[0:1], v[0:1] op_sel:[0,0]
	v_pk_mov_b32 v[34:35], v[0:1], v[0:1] op_sel:[0,0]
	v_pk_mov_b32 v[36:37], v[0:1], v[0:1] op_sel:[0,0]
	v_pk_mov_b32 v[38:39], v[0:1], v[0:1] op_sel:[0,0]
	v_pk_mov_b32 v[40:41], v[0:1], v[0:1] op_sel:[0,0]
	v_pk_mov_b32 v[42:43], v[0:1], v[0:1] op_sel:[0,0]
	v_pk_mov_b32 v[44:45], v[0:1], v[0:1] op_sel:[0,0]
	v_pk_mov_b32 v[46:47], v[0:1], v[0:1] op_sel:[0,0]
	v_pk_mov_b32 v[48:49], v[0:1], v[0:1] op_sel:[0,0]
	v_pk_mov_b32 v[50:51], v[0:1], v[0:1] op_sel:[0,0]
	v_pk_mov_b32 v[52:53], v[0:1], v[0:1] op_sel:[0,0]
	v_pk_mov_b32 v[54:55], v[0:1], v[0:1] op_sel:[0,0]
	v_pk_mov_b32 v[56:57], v[0:1], v[0:1] op_sel:[0,0]
	v_pk_mov_b32 v[58:59], v[0:1], v[0:1] op_sel:[0,0]
	v_pk_mov_b32 v[60:61], v[0:1], v[0:1] op_sel:[0,0]
	v_pk_mov_b32 v[62:63], v[0:1], v[0:1] op_sel:[0,0]
	v_pk_mov_b32 v[64:65], v[0:1], v[0:1] op_sel:[0,0]
	v_pk_mov_b32 v[66:67], v[0:1], v[0:1] op_sel:[0,0]
	v_pk_mov_b32 v[68:69], v[0:1], v[0:1] op_sel:[0,0]
	v_pk_mov_b32 v[70:71], v[0:1], v[0:1] op_sel:[0,0]
	v_pk_mov_b32 v[72:73], v[0:1], v[0:1] op_sel:[0,0]
	v_pk_mov_b32 v[74:75], v[0:1], v[0:1] op_sel:[0,0]
	v_pk_mov_b32 v[76:77], v[0:1], v[0:1] op_sel:[0,0]
	v_pk_mov_b32 v[78:79], v[0:1], v[0:1] op_sel:[0,0]
	v_pk_mov_b32 v[80:81], v[0:1], v[0:1] op_sel:[0,0]
	v_pk_mov_b32 v[82:83], v[0:1], v[0:1] op_sel:[0,0]
	v_pk_mov_b32 v[84:85], v[0:1], v[0:1] op_sel:[0,0]
	v_pk_mov_b32 v[86:87], v[0:1], v[0:1] op_sel:[0,0]
	v_pk_mov_b32 v[88:89], v[0:1], v[0:1] op_sel:[0,0]
	v_pk_mov_b32 v[90:91], v[0:1], v[0:1] op_sel:[0,0]
	v_pk_mov_b32 v[92:93], v[0:1], v[0:1] op_sel:[0,0]
	v_pk_mov_b32 v[94:95], v[0:1], v[0:1] op_sel:[0,0]
	v_pk_mov_b32 v[96:97], v[0:1], v[0:1] op_sel:[0,0]
	v_pk_mov_b32 v[98:99], v[0:1], v[0:1] op_sel:[0,0]
	v_pk_mov_b32 v[100:101], v[0:1], v[0:1] op_sel:[0,0]
	v_pk_mov_b32 v[102:103], v[0:1], v[0:1] op_sel:[0,0]
	v_pk_mov_b32 v[104:105], v[0:1], v[0:1] op_sel:[0,0]
	v_pk_mov_b32 v[106:107], v[0:1], v[0:1] op_sel:[0,0]
	v_pk_mov_b32 v[108:109], v[0:1], v[0:1] op_sel:[0,0]
	v_pk_mov_b32 v[110:111], v[0:1], v[0:1] op_sel:[0,0]
	v_pk_mov_b32 v[112:113], v[0:1], v[0:1] op_sel:[0,0]
	v_pk_mov_b32 v[114:115], v[0:1], v[0:1] op_sel:[0,0]
	v_pk_mov_b32 v[116:117], v[0:1], v[0:1] op_sel:[0,0]
	v_pk_mov_b32 v[118:119], v[0:1], v[0:1] op_sel:[0,0]
	v_pk_mov_b32 v[120:121], v[0:1], v[0:1] op_sel:[0,0]
	v_pk_mov_b32 v[122:123], v[0:1], v[0:1] op_sel:[0,0]
	v_pk_mov_b32 v[124:125], v[0:1], v[0:1] op_sel:[0,0]
	v_pk_mov_b32 v[126:127], v[0:1], v[0:1] op_sel:[0,0]

.LBB0_274:
	s_ashr_i32 s17, s16, 31
	s_lshl_b64 s[18:19], s[16:17], 19
	s_add_u32 s18, s27, s18
	s_addc_u32 s19, s28, s19
	s_and_b64 s[20:21], s[14:15], exec
	s_cselect_b32 s17, s19, s1
	s_cselect_b32 s49, s18, s0
	s_ashr_i32 s13, s12, 31
	s_lshl_b64 s[20:21], s[12:13], 19
	s_add_u32 s20, s29, s20
	s_addc_u32 s21, s30, s21
	s_and_b64 s[24:25], s[14:15], exec
	s_cselect_b32 s13, s21, s23
	s_cselect_b32 s50, s20, s22
	s_add_u32 s0, s0, 0x40080
	s_addc_u32 s1, s1, 0
	s_add_u32 s51, s22, 0x100
	v_mov_b32_e32 v0, 0
	s_addc_u32 s52, s23, 0
	s_mov_b32 s53, -2
	v_mov_b32_e32 v1, v0
	v_pk_mov_b32 v[2:3], v[0:1], v[0:1] op_sel:[0,0]
	v_pk_mov_b32 v[4:5], v[0:1], v[0:1] op_sel:[0,0]
	v_pk_mov_b32 v[6:7], v[0:1], v[0:1] op_sel:[0,0]
	v_pk_mov_b32 v[8:9], v[0:1], v[0:1] op_sel:[0,0]
	v_pk_mov_b32 v[10:11], v[0:1], v[0:1] op_sel:[0,0]
	v_pk_mov_b32 v[12:13], v[0:1], v[0:1] op_sel:[0,0]
	v_pk_mov_b32 v[14:15], v[0:1], v[0:1] op_sel:[0,0]
	v_pk_mov_b32 v[16:17], v[0:1], v[0:1] op_sel:[0,0]
	v_pk_mov_b32 v[18:19], v[0:1], v[0:1] op_sel:[0,0]
	v_pk_mov_b32 v[20:21], v[0:1], v[0:1] op_sel:[0,0]
	v_pk_mov_b32 v[22:23], v[0:1], v[0:1] op_sel:[0,0]
	v_pk_mov_b32 v[24:25], v[0:1], v[0:1] op_sel:[0,0]
	v_pk_mov_b32 v[26:27], v[0:1], v[0:1] op_sel:[0,0]
	v_pk_mov_b32 v[28:29], v[0:1], v[0:1] op_sel:[0,0]
	v_pk_mov_b32 v[30:31], v[0:1], v[0:1] op_sel:[0,0]
	v_pk_mov_b32 v[32:33], v[0:1], v[0:1] op_sel:[0,0]
	v_pk_mov_b32 v[34:35], v[0:1], v[0:1] op_sel:[0,0]
	v_pk_mov_b32 v[36:37], v[0:1], v[0:1] op_sel:[0,0]
	v_pk_mov_b32 v[38:39], v[0:1], v[0:1] op_sel:[0,0]
	v_pk_mov_b32 v[40:41], v[0:1], v[0:1] op_sel:[0,0]
	v_pk_mov_b32 v[42:43], v[0:1], v[0:1] op_sel:[0,0]
	v_pk_mov_b32 v[44:45], v[0:1], v[0:1] op_sel:[0,0]
	v_pk_mov_b32 v[46:47], v[0:1], v[0:1] op_sel:[0,0]
	v_pk_mov_b32 v[48:49], v[0:1], v[0:1] op_sel:[0,0]
	v_pk_mov_b32 v[50:51], v[0:1], v[0:1] op_sel:[0,0]
	v_pk_mov_b32 v[52:53], v[0:1], v[0:1] op_sel:[0,0]
	v_pk_mov_b32 v[54:55], v[0:1], v[0:1] op_sel:[0,0]
	v_pk_mov_b32 v[56:57], v[0:1], v[0:1] op_sel:[0,0]
	v_pk_mov_b32 v[58:59], v[0:1], v[0:1] op_sel:[0,0]
	v_pk_mov_b32 v[60:61], v[0:1], v[0:1] op_sel:[0,0]
	v_pk_mov_b32 v[62:63], v[0:1], v[0:1] op_sel:[0,0]
	v_pk_mov_b32 v[64:65], v[0:1], v[0:1] op_sel:[0,0]
	v_pk_mov_b32 v[66:67], v[0:1], v[0:1] op_sel:[0,0]
	v_pk_mov_b32 v[68:69], v[0:1], v[0:1] op_sel:[0,0]
	v_pk_mov_b32 v[70:71], v[0:1], v[0:1] op_sel:[0,0]
	v_pk_mov_b32 v[72:73], v[0:1], v[0:1] op_sel:[0,0]
	v_pk_mov_b32 v[74:75], v[0:1], v[0:1] op_sel:[0,0]
	v_pk_mov_b32 v[76:77], v[0:1], v[0:1] op_sel:[0,0]
	v_pk_mov_b32 v[78:79], v[0:1], v[0:1] op_sel:[0,0]
	v_pk_mov_b32 v[80:81], v[0:1], v[0:1] op_sel:[0,0]
	v_pk_mov_b32 v[82:83], v[0:1], v[0:1] op_sel:[0,0]
	v_pk_mov_b32 v[84:85], v[0:1], v[0:1] op_sel:[0,0]
	v_pk_mov_b32 v[86:87], v[0:1], v[0:1] op_sel:[0,0]
	v_pk_mov_b32 v[88:89], v[0:1], v[0:1] op_sel:[0,0]
	v_pk_mov_b32 v[90:91], v[0:1], v[0:1] op_sel:[0,0]
	v_pk_mov_b32 v[92:93], v[0:1], v[0:1] op_sel:[0,0]
	v_pk_mov_b32 v[94:95], v[0:1], v[0:1] op_sel:[0,0]
	v_pk_mov_b32 v[96:97], v[0:1], v[0:1] op_sel:[0,0]
	v_pk_mov_b32 v[98:99], v[0:1], v[0:1] op_sel:[0,0]
	v_pk_mov_b32 v[100:101], v[0:1], v[0:1] op_sel:[0,0]
	v_pk_mov_b32 v[102:103], v[0:1], v[0:1] op_sel:[0,0]
	v_pk_mov_b32 v[104:105], v[0:1], v[0:1] op_sel:[0,0]
	v_pk_mov_b32 v[106:107], v[0:1], v[0:1] op_sel:[0,0]
	v_pk_mov_b32 v[108:109], v[0:1], v[0:1] op_sel:[0,0]
	v_pk_mov_b32 v[110:111], v[0:1], v[0:1] op_sel:[0,0]
	v_pk_mov_b32 v[112:113], v[0:1], v[0:1] op_sel:[0,0]
	v_pk_mov_b32 v[114:115], v[0:1], v[0:1] op_sel:[0,0]
	v_pk_mov_b32 v[116:117], v[0:1], v[0:1] op_sel:[0,0]
	v_pk_mov_b32 v[118:119], v[0:1], v[0:1] op_sel:[0,0]
	v_pk_mov_b32 v[120:121], v[0:1], v[0:1] op_sel:[0,0]
	v_pk_mov_b32 v[122:123], v[0:1], v[0:1] op_sel:[0,0]
	v_pk_mov_b32 v[124:125], v[0:1], v[0:1] op_sel:[0,0]
	v_pk_mov_b32 v[126:127], v[0:1], v[0:1] op_sel:[0,0]

.LBB0_555:
	s_ashr_i32 s15, s14, 31
	s_lshl_b64 s[16:17], s[14:15], 19
	s_add_u32 s16, s90, s16
	s_addc_u32 s17, s91, s17
	s_and_b64 s[18:19], s[2:3], exec
	s_cselect_b32 s15, s17, s21
	s_cselect_b32 s46, s16, s20
	s_ashr_i32 s13, s12, 31
	s_lshl_b64 s[18:19], s[12:13], 19
	s_add_u32 s18, s26, s18
	s_addc_u32 s19, s27, s19
	s_and_b64 s[24:25], s[2:3], exec
	s_cselect_b32 s13, s19, s23
	s_cselect_b32 s47, s18, s22
	s_add_u32 s20, s20, 0x40080
	s_addc_u32 s21, s21, 0
	s_add_u32 s48, s22, 0x100
	v_mov_b32_e32 v0, 0
	s_addc_u32 s49, s23, 0
	s_mov_b32 s50, -2
	v_mov_b32_e32 v1, v0
	v_pk_mov_b32 v[2:3], v[0:1], v[0:1] op_sel:[0,0]
	v_pk_mov_b32 v[4:5], v[0:1], v[0:1] op_sel:[0,0]
	v_pk_mov_b32 v[6:7], v[0:1], v[0:1] op_sel:[0,0]
	v_pk_mov_b32 v[8:9], v[0:1], v[0:1] op_sel:[0,0]
	v_pk_mov_b32 v[10:11], v[0:1], v[0:1] op_sel:[0,0]
	v_pk_mov_b32 v[12:13], v[0:1], v[0:1] op_sel:[0,0]
	v_pk_mov_b32 v[14:15], v[0:1], v[0:1] op_sel:[0,0]
	v_pk_mov_b32 v[16:17], v[0:1], v[0:1] op_sel:[0,0]
	v_pk_mov_b32 v[18:19], v[0:1], v[0:1] op_sel:[0,0]
	v_pk_mov_b32 v[20:21], v[0:1], v[0:1] op_sel:[0,0]
	v_pk_mov_b32 v[22:23], v[0:1], v[0:1] op_sel:[0,0]
	v_pk_mov_b32 v[24:25], v[0:1], v[0:1] op_sel:[0,0]
	v_pk_mov_b32 v[26:27], v[0:1], v[0:1] op_sel:[0,0]
	v_pk_mov_b32 v[28:29], v[0:1], v[0:1] op_sel:[0,0]
	v_pk_mov_b32 v[30:31], v[0:1], v[0:1] op_sel:[0,0]
	v_pk_mov_b32 v[32:33], v[0:1], v[0:1] op_sel:[0,0]
	v_pk_mov_b32 v[34:35], v[0:1], v[0:1] op_sel:[0,0]
	v_pk_mov_b32 v[36:37], v[0:1], v[0:1] op_sel:[0,0]
	v_pk_mov_b32 v[38:39], v[0:1], v[0:1] op_sel:[0,0]
	v_pk_mov_b32 v[40:41], v[0:1], v[0:1] op_sel:[0,0]
	v_pk_mov_b32 v[42:43], v[0:1], v[0:1] op_sel:[0,0]
	v_pk_mov_b32 v[44:45], v[0:1], v[0:1] op_sel:[0,0]
	v_pk_mov_b32 v[46:47], v[0:1], v[0:1] op_sel:[0,0]
	v_pk_mov_b32 v[48:49], v[0:1], v[0:1] op_sel:[0,0]
	v_pk_mov_b32 v[50:51], v[0:1], v[0:1] op_sel:[0,0]
	v_pk_mov_b32 v[52:53], v[0:1], v[0:1] op_sel:[0,0]
	v_pk_mov_b32 v[54:55], v[0:1], v[0:1] op_sel:[0,0]
	v_pk_mov_b32 v[56:57], v[0:1], v[0:1] op_sel:[0,0]
	v_pk_mov_b32 v[58:59], v[0:1], v[0:1] op_sel:[0,0]
	v_pk_mov_b32 v[60:61], v[0:1], v[0:1] op_sel:[0,0]
	v_pk_mov_b32 v[62:63], v[0:1], v[0:1] op_sel:[0,0]
	v_pk_mov_b32 v[64:65], v[0:1], v[0:1] op_sel:[0,0]
	v_pk_mov_b32 v[66:67], v[0:1], v[0:1] op_sel:[0,0]
	v_pk_mov_b32 v[68:69], v[0:1], v[0:1] op_sel:[0,0]
	v_pk_mov_b32 v[70:71], v[0:1], v[0:1] op_sel:[0,0]
	v_pk_mov_b32 v[72:73], v[0:1], v[0:1] op_sel:[0,0]
	v_pk_mov_b32 v[74:75], v[0:1], v[0:1] op_sel:[0,0]
	v_pk_mov_b32 v[76:77], v[0:1], v[0:1] op_sel:[0,0]
	v_pk_mov_b32 v[78:79], v[0:1], v[0:1] op_sel:[0,0]
	v_pk_mov_b32 v[80:81], v[0:1], v[0:1] op_sel:[0,0]
	v_pk_mov_b32 v[82:83], v[0:1], v[0:1] op_sel:[0,0]
	v_pk_mov_b32 v[84:85], v[0:1], v[0:1] op_sel:[0,0]
	v_pk_mov_b32 v[86:87], v[0:1], v[0:1] op_sel:[0,0]
	v_pk_mov_b32 v[88:89], v[0:1], v[0:1] op_sel:[0,0]
	v_pk_mov_b32 v[90:91], v[0:1], v[0:1] op_sel:[0,0]
	v_pk_mov_b32 v[92:93], v[0:1], v[0:1] op_sel:[0,0]
	v_pk_mov_b32 v[94:95], v[0:1], v[0:1] op_sel:[0,0]
	v_pk_mov_b32 v[96:97], v[0:1], v[0:1] op_sel:[0,0]
	v_pk_mov_b32 v[98:99], v[0:1], v[0:1] op_sel:[0,0]
	v_pk_mov_b32 v[100:101], v[0:1], v[0:1] op_sel:[0,0]
	v_pk_mov_b32 v[102:103], v[0:1], v[0:1] op_sel:[0,0]
	v_pk_mov_b32 v[104:105], v[0:1], v[0:1] op_sel:[0,0]
	v_pk_mov_b32 v[106:107], v[0:1], v[0:1] op_sel:[0,0]
	v_pk_mov_b32 v[108:109], v[0:1], v[0:1] op_sel:[0,0]
	v_pk_mov_b32 v[110:111], v[0:1], v[0:1] op_sel:[0,0]
	v_pk_mov_b32 v[112:113], v[0:1], v[0:1] op_sel:[0,0]
	v_pk_mov_b32 v[114:115], v[0:1], v[0:1] op_sel:[0,0]
	v_pk_mov_b32 v[116:117], v[0:1], v[0:1] op_sel:[0,0]
	v_pk_mov_b32 v[118:119], v[0:1], v[0:1] op_sel:[0,0]
	v_pk_mov_b32 v[120:121], v[0:1], v[0:1] op_sel:[0,0]
	v_pk_mov_b32 v[122:123], v[0:1], v[0:1] op_sel:[0,0]
	v_pk_mov_b32 v[124:125], v[0:1], v[0:1] op_sel:[0,0]
	v_pk_mov_b32 v[126:127], v[0:1], v[0:1] op_sel:[0,0]

.LBB0_627:
	s_ashr_i32 s19, s18, 31
	v_readlane_b32 s48, v254, 32
	s_lshl_b64 s[20:21], s[18:19], 20
	v_readlane_b32 s62, v254, 46
	v_readlane_b32 s63, v254, 47
	s_add_u32 s20, s62, s20
	s_addc_u32 s21, s63, s21
	s_and_b64 s[22:23], s[2:3], exec
	s_cselect_b32 s19, s21, s25
	s_cselect_b32 s47, s20, s24
	s_ashr_i32 s17, s16, 31
	s_lshl_b64 s[22:23], s[16:17], 20
	s_add_u32 s22, s6, s22
	s_addc_u32 s23, s7, s23
	s_and_b64 s[28:29], s[2:3], exec
	s_cselect_b32 s17, s23, s27
	s_cselect_b32 s48, s22, s26
	s_add_u32 s24, s24, 0x80080
	v_readlane_b32 s49, v254, 33
	s_addc_u32 s25, s25, 0
	v_readlane_b32 s50, v254, 34
	v_readlane_b32 s51, v254, 35
	s_add_u32 s49, s26, 0x100
	v_mov_b32_e32 v0, 0
	s_addc_u32 s50, s27, 0
	s_mov_b32 s51, -2
	v_mov_b32_e32 v1, v0
	v_pk_mov_b32 v[2:3], v[0:1], v[0:1] op_sel:[0,0]
	v_pk_mov_b32 v[4:5], v[0:1], v[0:1] op_sel:[0,0]
	v_pk_mov_b32 v[6:7], v[0:1], v[0:1] op_sel:[0,0]
	v_pk_mov_b32 v[8:9], v[0:1], v[0:1] op_sel:[0,0]
	v_pk_mov_b32 v[10:11], v[0:1], v[0:1] op_sel:[0,0]
	v_pk_mov_b32 v[12:13], v[0:1], v[0:1] op_sel:[0,0]
	v_pk_mov_b32 v[14:15], v[0:1], v[0:1] op_sel:[0,0]
	v_pk_mov_b32 v[16:17], v[0:1], v[0:1] op_sel:[0,0]
	v_pk_mov_b32 v[18:19], v[0:1], v[0:1] op_sel:[0,0]
	v_pk_mov_b32 v[20:21], v[0:1], v[0:1] op_sel:[0,0]
	v_pk_mov_b32 v[22:23], v[0:1], v[0:1] op_sel:[0,0]
	v_pk_mov_b32 v[24:25], v[0:1], v[0:1] op_sel:[0,0]
	v_pk_mov_b32 v[26:27], v[0:1], v[0:1] op_sel:[0,0]
	v_pk_mov_b32 v[28:29], v[0:1], v[0:1] op_sel:[0,0]
	v_pk_mov_b32 v[30:31], v[0:1], v[0:1] op_sel:[0,0]
	v_pk_mov_b32 v[32:33], v[0:1], v[0:1] op_sel:[0,0]
	v_pk_mov_b32 v[34:35], v[0:1], v[0:1] op_sel:[0,0]
	v_pk_mov_b32 v[36:37], v[0:1], v[0:1] op_sel:[0,0]
	v_pk_mov_b32 v[38:39], v[0:1], v[0:1] op_sel:[0,0]
	v_pk_mov_b32 v[40:41], v[0:1], v[0:1] op_sel:[0,0]
	v_pk_mov_b32 v[42:43], v[0:1], v[0:1] op_sel:[0,0]
	v_pk_mov_b32 v[44:45], v[0:1], v[0:1] op_sel:[0,0]
	v_pk_mov_b32 v[46:47], v[0:1], v[0:1] op_sel:[0,0]
	v_pk_mov_b32 v[48:49], v[0:1], v[0:1] op_sel:[0,0]
	v_pk_mov_b32 v[50:51], v[0:1], v[0:1] op_sel:[0,0]
	v_pk_mov_b32 v[52:53], v[0:1], v[0:1] op_sel:[0,0]
	v_pk_mov_b32 v[54:55], v[0:1], v[0:1] op_sel:[0,0]
	v_pk_mov_b32 v[56:57], v[0:1], v[0:1] op_sel:[0,0]
	v_pk_mov_b32 v[58:59], v[0:1], v[0:1] op_sel:[0,0]
	v_pk_mov_b32 v[60:61], v[0:1], v[0:1] op_sel:[0,0]
	v_pk_mov_b32 v[62:63], v[0:1], v[0:1] op_sel:[0,0]
	v_pk_mov_b32 v[64:65], v[0:1], v[0:1] op_sel:[0,0]
	v_pk_mov_b32 v[66:67], v[0:1], v[0:1] op_sel:[0,0]
	v_pk_mov_b32 v[68:69], v[0:1], v[0:1] op_sel:[0,0]
	v_pk_mov_b32 v[70:71], v[0:1], v[0:1] op_sel:[0,0]
	v_pk_mov_b32 v[72:73], v[0:1], v[0:1] op_sel:[0,0]
	v_pk_mov_b32 v[74:75], v[0:1], v[0:1] op_sel:[0,0]
	v_pk_mov_b32 v[76:77], v[0:1], v[0:1] op_sel:[0,0]
	v_pk_mov_b32 v[78:79], v[0:1], v[0:1] op_sel:[0,0]
	v_pk_mov_b32 v[80:81], v[0:1], v[0:1] op_sel:[0,0]
	v_pk_mov_b32 v[82:83], v[0:1], v[0:1] op_sel:[0,0]
	v_pk_mov_b32 v[84:85], v[0:1], v[0:1] op_sel:[0,0]
	v_pk_mov_b32 v[86:87], v[0:1], v[0:1] op_sel:[0,0]
	v_pk_mov_b32 v[88:89], v[0:1], v[0:1] op_sel:[0,0]
	v_pk_mov_b32 v[90:91], v[0:1], v[0:1] op_sel:[0,0]
	v_pk_mov_b32 v[92:93], v[0:1], v[0:1] op_sel:[0,0]
	v_pk_mov_b32 v[94:95], v[0:1], v[0:1] op_sel:[0,0]
	v_pk_mov_b32 v[96:97], v[0:1], v[0:1] op_sel:[0,0]
	v_pk_mov_b32 v[98:99], v[0:1], v[0:1] op_sel:[0,0]
	v_pk_mov_b32 v[100:101], v[0:1], v[0:1] op_sel:[0,0]
	v_pk_mov_b32 v[102:103], v[0:1], v[0:1] op_sel:[0,0]
	v_pk_mov_b32 v[104:105], v[0:1], v[0:1] op_sel:[0,0]
	v_pk_mov_b32 v[106:107], v[0:1], v[0:1] op_sel:[0,0]
	v_pk_mov_b32 v[108:109], v[0:1], v[0:1] op_sel:[0,0]
	v_pk_mov_b32 v[110:111], v[0:1], v[0:1] op_sel:[0,0]
	v_pk_mov_b32 v[112:113], v[0:1], v[0:1] op_sel:[0,0]
	v_pk_mov_b32 v[114:115], v[0:1], v[0:1] op_sel:[0,0]
	v_pk_mov_b32 v[116:117], v[0:1], v[0:1] op_sel:[0,0]
	v_pk_mov_b32 v[118:119], v[0:1], v[0:1] op_sel:[0,0]
	v_pk_mov_b32 v[120:121], v[0:1], v[0:1] op_sel:[0,0]
	v_pk_mov_b32 v[122:123], v[0:1], v[0:1] op_sel:[0,0]
	v_pk_mov_b32 v[124:125], v[0:1], v[0:1] op_sel:[0,0]
	v_pk_mov_b32 v[126:127], v[0:1], v[0:1] op_sel:[0,0]
	v_readlane_b32 s52, v254, 36
	v_readlane_b32 s53, v254, 37
	v_readlane_b32 s54, v254, 38
	v_readlane_b32 s55, v254, 39
	v_readlane_b32 s56, v254, 40
	v_readlane_b32 s57, v254, 41
	v_readlane_b32 s58, v254, 42
	v_readlane_b32 s59, v254, 43
	v_readlane_b32 s60, v254, 44
	v_readlane_b32 s61, v254, 45

.LBB0_714:
	s_ashr_i32 s23, s22, 31
	s_lshl_b64 s[24:25], s[22:23], 19
	s_add_u32 s24, s12, s24
	s_addc_u32 s25, s13, s25
	s_and_b64 s[26:27], s[2:3], exec
	s_cselect_b32 s23, s25, s29
	s_cselect_b32 s50, s24, s28
	s_ashr_i32 s21, s20, 31
	s_lshl_b64 s[26:27], s[20:21], 19
	s_add_u32 s26, s10, s26
	s_addc_u32 s27, s11, s27
	s_and_b64 s[34:35], s[2:3], exec
	s_cselect_b32 s21, s27, s31
	s_cselect_b32 s51, s26, s30
	s_add_u32 s28, s28, 0x40080
	s_addc_u32 s29, s29, 0
	s_add_u32 s52, s30, 0x100
	v_mov_b32_e32 v0, 0
	s_addc_u32 s53, s31, 0
	s_mov_b32 s54, -2
	v_mov_b32_e32 v1, v0
	v_pk_mov_b32 v[2:3], v[0:1], v[0:1] op_sel:[0,0]
	v_pk_mov_b32 v[4:5], v[0:1], v[0:1] op_sel:[0,0]
	v_pk_mov_b32 v[6:7], v[0:1], v[0:1] op_sel:[0,0]
	v_pk_mov_b32 v[8:9], v[0:1], v[0:1] op_sel:[0,0]
	v_pk_mov_b32 v[10:11], v[0:1], v[0:1] op_sel:[0,0]
	v_pk_mov_b32 v[12:13], v[0:1], v[0:1] op_sel:[0,0]
	v_pk_mov_b32 v[14:15], v[0:1], v[0:1] op_sel:[0,0]
	v_pk_mov_b32 v[16:17], v[0:1], v[0:1] op_sel:[0,0]
	v_pk_mov_b32 v[18:19], v[0:1], v[0:1] op_sel:[0,0]
	v_pk_mov_b32 v[20:21], v[0:1], v[0:1] op_sel:[0,0]
	v_pk_mov_b32 v[22:23], v[0:1], v[0:1] op_sel:[0,0]
	v_pk_mov_b32 v[24:25], v[0:1], v[0:1] op_sel:[0,0]
	v_pk_mov_b32 v[26:27], v[0:1], v[0:1] op_sel:[0,0]
	v_pk_mov_b32 v[28:29], v[0:1], v[0:1] op_sel:[0,0]
	v_pk_mov_b32 v[30:31], v[0:1], v[0:1] op_sel:[0,0]
	v_pk_mov_b32 v[32:33], v[0:1], v[0:1] op_sel:[0,0]
	v_pk_mov_b32 v[34:35], v[0:1], v[0:1] op_sel:[0,0]
	v_pk_mov_b32 v[36:37], v[0:1], v[0:1] op_sel:[0,0]
	v_pk_mov_b32 v[38:39], v[0:1], v[0:1] op_sel:[0,0]
	v_pk_mov_b32 v[40:41], v[0:1], v[0:1] op_sel:[0,0]
	v_pk_mov_b32 v[42:43], v[0:1], v[0:1] op_sel:[0,0]
	v_pk_mov_b32 v[44:45], v[0:1], v[0:1] op_sel:[0,0]
	v_pk_mov_b32 v[46:47], v[0:1], v[0:1] op_sel:[0,0]
	v_pk_mov_b32 v[48:49], v[0:1], v[0:1] op_sel:[0,0]
	v_pk_mov_b32 v[50:51], v[0:1], v[0:1] op_sel:[0,0]
	v_pk_mov_b32 v[52:53], v[0:1], v[0:1] op_sel:[0,0]
	v_pk_mov_b32 v[54:55], v[0:1], v[0:1] op_sel:[0,0]
	v_pk_mov_b32 v[56:57], v[0:1], v[0:1] op_sel:[0,0]
	v_pk_mov_b32 v[58:59], v[0:1], v[0:1] op_sel:[0,0]
	v_pk_mov_b32 v[60:61], v[0:1], v[0:1] op_sel:[0,0]
	v_pk_mov_b32 v[62:63], v[0:1], v[0:1] op_sel:[0,0]
	v_pk_mov_b32 v[64:65], v[0:1], v[0:1] op_sel:[0,0]
	v_pk_mov_b32 v[66:67], v[0:1], v[0:1] op_sel:[0,0]
	v_pk_mov_b32 v[68:69], v[0:1], v[0:1] op_sel:[0,0]
	v_pk_mov_b32 v[70:71], v[0:1], v[0:1] op_sel:[0,0]
	v_pk_mov_b32 v[72:73], v[0:1], v[0:1] op_sel:[0,0]
	v_pk_mov_b32 v[74:75], v[0:1], v[0:1] op_sel:[0,0]
	v_pk_mov_b32 v[76:77], v[0:1], v[0:1] op_sel:[0,0]
	v_pk_mov_b32 v[78:79], v[0:1], v[0:1] op_sel:[0,0]
	v_pk_mov_b32 v[80:81], v[0:1], v[0:1] op_sel:[0,0]
	v_pk_mov_b32 v[82:83], v[0:1], v[0:1] op_sel:[0,0]
	v_pk_mov_b32 v[84:85], v[0:1], v[0:1] op_sel:[0,0]
	v_pk_mov_b32 v[86:87], v[0:1], v[0:1] op_sel:[0,0]
	v_pk_mov_b32 v[88:89], v[0:1], v[0:1] op_sel:[0,0]
	v_pk_mov_b32 v[90:91], v[0:1], v[0:1] op_sel:[0,0]
	v_pk_mov_b32 v[92:93], v[0:1], v[0:1] op_sel:[0,0]
	v_pk_mov_b32 v[94:95], v[0:1], v[0:1] op_sel:[0,0]
	v_pk_mov_b32 v[96:97], v[0:1], v[0:1] op_sel:[0,0]
	v_pk_mov_b32 v[98:99], v[0:1], v[0:1] op_sel:[0,0]
	v_pk_mov_b32 v[100:101], v[0:1], v[0:1] op_sel:[0,0]
	v_pk_mov_b32 v[102:103], v[0:1], v[0:1] op_sel:[0,0]
	v_pk_mov_b32 v[104:105], v[0:1], v[0:1] op_sel:[0,0]
	v_pk_mov_b32 v[106:107], v[0:1], v[0:1] op_sel:[0,0]
	v_pk_mov_b32 v[108:109], v[0:1], v[0:1] op_sel:[0,0]
	v_pk_mov_b32 v[110:111], v[0:1], v[0:1] op_sel:[0,0]
	v_pk_mov_b32 v[112:113], v[0:1], v[0:1] op_sel:[0,0]
	v_pk_mov_b32 v[114:115], v[0:1], v[0:1] op_sel:[0,0]
	v_pk_mov_b32 v[116:117], v[0:1], v[0:1] op_sel:[0,0]
	v_pk_mov_b32 v[118:119], v[0:1], v[0:1] op_sel:[0,0]
	v_pk_mov_b32 v[120:121], v[0:1], v[0:1] op_sel:[0,0]
	v_pk_mov_b32 v[122:123], v[0:1], v[0:1] op_sel:[0,0]
	v_pk_mov_b32 v[124:125], v[0:1], v[0:1] op_sel:[0,0]
	v_pk_mov_b32 v[126:127], v[0:1], v[0:1] op_sel:[0,0]

.LBB0_910:
	s_ashr_i32 s31, s30, 31
	s_lshl_b64 s[34:35], s[30:31], 19
	s_add_u32 s34, s0, s34
	s_addc_u32 s35, s1, s35
	s_and_b64 s[36:37], s[6:7], exec
	s_cselect_b32 s31, s35, s43
	s_cselect_b32 s39, s34, s42
	s_ashr_i32 s29, s28, 31
	s_lshl_b64 s[36:37], s[28:29], 19
	s_add_u32 s36, s33, s36
	s_addc_u32 s37, s48, s37
	s_and_b64 s[46:47], s[6:7], exec
	s_cselect_b32 s29, s37, s45
	s_cselect_b32 s64, s36, s44
	s_add_u32 s42, s42, 0x40080
	s_addc_u32 s43, s43, 0
	s_add_u32 s65, s44, 0x100
	v_mov_b32_e32 v0, 0
	s_addc_u32 s66, s45, 0
	s_mov_b32 s67, -2
	v_mov_b32_e32 v1, v0
	v_mov_b32_e32 v2, v0
	v_mov_b32_e32 v3, v0
	v_mov_b32_e32 v4, v0
	s_waitcnt lgkmcnt(0)
	v_mov_b32_e32 v5, v0
	v_pk_mov_b32 v[6:7], v[0:1], v[0:1] op_sel:[0,0]
	v_pk_mov_b32 v[8:9], v[0:1], v[0:1] op_sel:[0,0]
	v_pk_mov_b32 v[10:11], v[0:1], v[0:1] op_sel:[0,0]
	v_pk_mov_b32 v[12:13], v[0:1], v[0:1] op_sel:[0,0]
	v_pk_mov_b32 v[14:15], v[0:1], v[0:1] op_sel:[0,0]
	v_pk_mov_b32 v[16:17], v[0:1], v[0:1] op_sel:[0,0]
	v_pk_mov_b32 v[18:19], v[0:1], v[0:1] op_sel:[0,0]
	v_pk_mov_b32 v[20:21], v[0:1], v[0:1] op_sel:[0,0]
	v_pk_mov_b32 v[22:23], v[0:1], v[0:1] op_sel:[0,0]
	v_pk_mov_b32 v[24:25], v[0:1], v[0:1] op_sel:[0,0]
	v_pk_mov_b32 v[26:27], v[0:1], v[0:1] op_sel:[0,0]
	v_pk_mov_b32 v[28:29], v[0:1], v[0:1] op_sel:[0,0]
	v_pk_mov_b32 v[30:31], v[0:1], v[0:1] op_sel:[0,0]
	v_pk_mov_b32 v[32:33], v[0:1], v[0:1] op_sel:[0,0]
	v_pk_mov_b32 v[34:35], v[0:1], v[0:1] op_sel:[0,0]
	v_pk_mov_b32 v[36:37], v[0:1], v[0:1] op_sel:[0,0]
	v_pk_mov_b32 v[38:39], v[0:1], v[0:1] op_sel:[0,0]
	v_pk_mov_b32 v[40:41], v[0:1], v[0:1] op_sel:[0,0]
	v_pk_mov_b32 v[42:43], v[0:1], v[0:1] op_sel:[0,0]
	v_pk_mov_b32 v[44:45], v[0:1], v[0:1] op_sel:[0,0]
	v_pk_mov_b32 v[46:47], v[0:1], v[0:1] op_sel:[0,0]
	v_pk_mov_b32 v[48:49], v[0:1], v[0:1] op_sel:[0,0]
	v_pk_mov_b32 v[50:51], v[0:1], v[0:1] op_sel:[0,0]
	v_pk_mov_b32 v[52:53], v[0:1], v[0:1] op_sel:[0,0]
	v_pk_mov_b32 v[54:55], v[0:1], v[0:1] op_sel:[0,0]
	v_pk_mov_b32 v[56:57], v[0:1], v[0:1] op_sel:[0,0]
	v_pk_mov_b32 v[58:59], v[0:1], v[0:1] op_sel:[0,0]
	v_pk_mov_b32 v[60:61], v[0:1], v[0:1] op_sel:[0,0]
	v_pk_mov_b32 v[62:63], v[0:1], v[0:1] op_sel:[0,0]
	v_pk_mov_b32 v[64:65], v[0:1], v[0:1] op_sel:[0,0]
	v_pk_mov_b32 v[66:67], v[0:1], v[0:1] op_sel:[0,0]
	v_pk_mov_b32 v[68:69], v[0:1], v[0:1] op_sel:[0,0]
	v_pk_mov_b32 v[70:71], v[0:1], v[0:1] op_sel:[0,0]
	v_pk_mov_b32 v[72:73], v[0:1], v[0:1] op_sel:[0,0]
	v_pk_mov_b32 v[74:75], v[0:1], v[0:1] op_sel:[0,0]
	v_pk_mov_b32 v[76:77], v[0:1], v[0:1] op_sel:[0,0]
	v_pk_mov_b32 v[78:79], v[0:1], v[0:1] op_sel:[0,0]
	v_pk_mov_b32 v[80:81], v[0:1], v[0:1] op_sel:[0,0]
	v_pk_mov_b32 v[82:83], v[0:1], v[0:1] op_sel:[0,0]
	v_pk_mov_b32 v[84:85], v[0:1], v[0:1] op_sel:[0,0]
	v_pk_mov_b32 v[86:87], v[0:1], v[0:1] op_sel:[0,0]
	v_pk_mov_b32 v[88:89], v[0:1], v[0:1] op_sel:[0,0]
	v_pk_mov_b32 v[90:91], v[0:1], v[0:1] op_sel:[0,0]
	v_pk_mov_b32 v[92:93], v[0:1], v[0:1] op_sel:[0,0]
	v_pk_mov_b32 v[94:95], v[0:1], v[0:1] op_sel:[0,0]
	v_pk_mov_b32 v[96:97], v[0:1], v[0:1] op_sel:[0,0]
	v_pk_mov_b32 v[98:99], v[0:1], v[0:1] op_sel:[0,0]
	v_pk_mov_b32 v[100:101], v[0:1], v[0:1] op_sel:[0,0]
	v_pk_mov_b32 v[102:103], v[0:1], v[0:1] op_sel:[0,0]
	v_pk_mov_b32 v[104:105], v[0:1], v[0:1] op_sel:[0,0]
	v_pk_mov_b32 v[106:107], v[0:1], v[0:1] op_sel:[0,0]
	v_pk_mov_b32 v[108:109], v[0:1], v[0:1] op_sel:[0,0]
	v_pk_mov_b32 v[110:111], v[0:1], v[0:1] op_sel:[0,0]
	v_pk_mov_b32 v[112:113], v[0:1], v[0:1] op_sel:[0,0]
	v_pk_mov_b32 v[114:115], v[0:1], v[0:1] op_sel:[0,0]
	v_pk_mov_b32 v[116:117], v[0:1], v[0:1] op_sel:[0,0]
	v_pk_mov_b32 v[118:119], v[0:1], v[0:1] op_sel:[0,0]
	v_pk_mov_b32 v[120:121], v[0:1], v[0:1] op_sel:[0,0]
	v_pk_mov_b32 v[122:123], v[0:1], v[0:1] op_sel:[0,0]
	v_pk_mov_b32 v[124:125], v[0:1], v[0:1] op_sel:[0,0]
	v_pk_mov_b32 v[126:127], v[0:1], v[0:1] op_sel:[0,0]

.LBB0_1079:
	s_ashr_i32 s27, s26, 31
	s_lshl_b64 s[28:29], s[26:27], 19
	s_add_u32 s28, s90, s28
	s_addc_u32 s29, s91, s29
	s_and_b64 s[30:31], s[4:5], exec
	s_cselect_b32 s27, s29, s35
	s_cselect_b32 s60, s28, s34
	s_ashr_i32 s25, s24, 31
	s_lshl_b64 s[30:31], s[24:25], 19
	s_add_u32 s30, s33, s30
	s_addc_u32 s31, s40, s31
	s_and_b64 s[38:39], s[4:5], exec
	s_cselect_b32 s25, s31, s37
	s_cselect_b32 s61, s30, s36
	s_add_u32 s34, s34, 0x40080
	s_addc_u32 s35, s35, 0
	s_add_u32 s62, s36, 0x100
	v_mov_b32_e32 v0, 0
	s_addc_u32 s63, s37, 0
	s_mov_b32 s64, -2
	v_mov_b32_e32 v1, v0
	v_pk_mov_b32 v[2:3], v[0:1], v[0:1] op_sel:[0,0]
	v_pk_mov_b32 v[4:5], v[0:1], v[0:1] op_sel:[0,0]
	v_pk_mov_b32 v[6:7], v[0:1], v[0:1] op_sel:[0,0]
	v_pk_mov_b32 v[8:9], v[0:1], v[0:1] op_sel:[0,0]
	v_pk_mov_b32 v[10:11], v[0:1], v[0:1] op_sel:[0,0]
	v_pk_mov_b32 v[12:13], v[0:1], v[0:1] op_sel:[0,0]
	v_pk_mov_b32 v[14:15], v[0:1], v[0:1] op_sel:[0,0]
	v_pk_mov_b32 v[16:17], v[0:1], v[0:1] op_sel:[0,0]
	v_pk_mov_b32 v[18:19], v[0:1], v[0:1] op_sel:[0,0]
	v_pk_mov_b32 v[20:21], v[0:1], v[0:1] op_sel:[0,0]
	v_pk_mov_b32 v[22:23], v[0:1], v[0:1] op_sel:[0,0]
	v_pk_mov_b32 v[24:25], v[0:1], v[0:1] op_sel:[0,0]
	v_pk_mov_b32 v[26:27], v[0:1], v[0:1] op_sel:[0,0]
	v_pk_mov_b32 v[28:29], v[0:1], v[0:1] op_sel:[0,0]
	v_pk_mov_b32 v[30:31], v[0:1], v[0:1] op_sel:[0,0]
	v_pk_mov_b32 v[32:33], v[0:1], v[0:1] op_sel:[0,0]
	v_pk_mov_b32 v[34:35], v[0:1], v[0:1] op_sel:[0,0]
	v_pk_mov_b32 v[36:37], v[0:1], v[0:1] op_sel:[0,0]
	v_pk_mov_b32 v[38:39], v[0:1], v[0:1] op_sel:[0,0]
	v_pk_mov_b32 v[40:41], v[0:1], v[0:1] op_sel:[0,0]
	v_pk_mov_b32 v[42:43], v[0:1], v[0:1] op_sel:[0,0]
	v_pk_mov_b32 v[44:45], v[0:1], v[0:1] op_sel:[0,0]
	v_pk_mov_b32 v[46:47], v[0:1], v[0:1] op_sel:[0,0]
	v_pk_mov_b32 v[48:49], v[0:1], v[0:1] op_sel:[0,0]
	v_pk_mov_b32 v[50:51], v[0:1], v[0:1] op_sel:[0,0]
	v_pk_mov_b32 v[52:53], v[0:1], v[0:1] op_sel:[0,0]
	v_pk_mov_b32 v[54:55], v[0:1], v[0:1] op_sel:[0,0]
	v_pk_mov_b32 v[56:57], v[0:1], v[0:1] op_sel:[0,0]
	v_pk_mov_b32 v[58:59], v[0:1], v[0:1] op_sel:[0,0]
	v_pk_mov_b32 v[60:61], v[0:1], v[0:1] op_sel:[0,0]
	v_pk_mov_b32 v[62:63], v[0:1], v[0:1] op_sel:[0,0]
	v_pk_mov_b32 v[64:65], v[0:1], v[0:1] op_sel:[0,0]
	v_pk_mov_b32 v[66:67], v[0:1], v[0:1] op_sel:[0,0]
	v_pk_mov_b32 v[68:69], v[0:1], v[0:1] op_sel:[0,0]
	v_pk_mov_b32 v[70:71], v[0:1], v[0:1] op_sel:[0,0]
	v_pk_mov_b32 v[72:73], v[0:1], v[0:1] op_sel:[0,0]
	v_pk_mov_b32 v[74:75], v[0:1], v[0:1] op_sel:[0,0]
	v_pk_mov_b32 v[76:77], v[0:1], v[0:1] op_sel:[0,0]
	v_pk_mov_b32 v[78:79], v[0:1], v[0:1] op_sel:[0,0]
	v_pk_mov_b32 v[80:81], v[0:1], v[0:1] op_sel:[0,0]
	v_pk_mov_b32 v[82:83], v[0:1], v[0:1] op_sel:[0,0]
	v_pk_mov_b32 v[84:85], v[0:1], v[0:1] op_sel:[0,0]
	v_pk_mov_b32 v[86:87], v[0:1], v[0:1] op_sel:[0,0]
	v_pk_mov_b32 v[88:89], v[0:1], v[0:1] op_sel:[0,0]
	v_pk_mov_b32 v[90:91], v[0:1], v[0:1] op_sel:[0,0]
	v_pk_mov_b32 v[92:93], v[0:1], v[0:1] op_sel:[0,0]
	v_pk_mov_b32 v[94:95], v[0:1], v[0:1] op_sel:[0,0]
	v_pk_mov_b32 v[96:97], v[0:1], v[0:1] op_sel:[0,0]
	v_pk_mov_b32 v[98:99], v[0:1], v[0:1] op_sel:[0,0]
	v_pk_mov_b32 v[100:101], v[0:1], v[0:1] op_sel:[0,0]
	v_pk_mov_b32 v[102:103], v[0:1], v[0:1] op_sel:[0,0]
	v_pk_mov_b32 v[104:105], v[0:1], v[0:1] op_sel:[0,0]
	v_pk_mov_b32 v[106:107], v[0:1], v[0:1] op_sel:[0,0]
	v_pk_mov_b32 v[108:109], v[0:1], v[0:1] op_sel:[0,0]
	v_pk_mov_b32 v[110:111], v[0:1], v[0:1] op_sel:[0,0]
	v_pk_mov_b32 v[112:113], v[0:1], v[0:1] op_sel:[0,0]
	v_pk_mov_b32 v[114:115], v[0:1], v[0:1] op_sel:[0,0]
	v_pk_mov_b32 v[116:117], v[0:1], v[0:1] op_sel:[0,0]
	v_pk_mov_b32 v[118:119], v[0:1], v[0:1] op_sel:[0,0]
	v_pk_mov_b32 v[120:121], v[0:1], v[0:1] op_sel:[0,0]
	v_pk_mov_b32 v[122:123], v[0:1], v[0:1] op_sel:[0,0]
	v_pk_mov_b32 v[124:125], v[0:1], v[0:1] op_sel:[0,0]
	v_pk_mov_b32 v[126:127], v[0:1], v[0:1] op_sel:[0,0]

.LBB0_1153:
	s_ashr_i32 s17, s16, 31
	s_lshl_b64 s[18:19], s[16:17], 21
	s_add_u32 s18, s92, s18
	s_addc_u32 s19, s93, s19
	s_and_b64 s[20:21], s[4:5], exec
	s_cselect_b32 s17, s19, s27
	s_cselect_b32 s23, s18, s26
	s_ashr_i32 s11, s10, 31
	s_lshl_b64 s[20:21], s[10:11], 21
	s_add_u32 s20, s33, s20
	s_addc_u32 s21, s50, s21
	s_and_b64 s[30:31], s[4:5], exec
	s_cselect_b32 s11, s21, s29
	s_cselect_b32 s45, s20, s28
	s_add_u32 s26, s26, 0x100080
	s_addc_u32 s27, s27, 0
	s_add_u32 s46, s28, 0x100
	v_mov_b32_e32 v0, 0
	s_addc_u32 s47, s29, 0
	s_mov_b32 s48, -2
	v_mov_b32_e32 v1, v0
	v_mov_b32_e32 v2, v0
	v_mov_b32_e32 v3, v0
	v_mov_b32_e32 v4, v0
	s_waitcnt lgkmcnt(0)
	v_mov_b32_e32 v5, v0
	v_pk_mov_b32 v[6:7], v[0:1], v[0:1] op_sel:[0,0]
	v_pk_mov_b32 v[8:9], v[0:1], v[0:1] op_sel:[0,0]
	v_pk_mov_b32 v[10:11], v[0:1], v[0:1] op_sel:[0,0]
	v_pk_mov_b32 v[12:13], v[0:1], v[0:1] op_sel:[0,0]
	v_pk_mov_b32 v[14:15], v[0:1], v[0:1] op_sel:[0,0]
	v_pk_mov_b32 v[16:17], v[0:1], v[0:1] op_sel:[0,0]
	v_pk_mov_b32 v[18:19], v[0:1], v[0:1] op_sel:[0,0]
	v_pk_mov_b32 v[20:21], v[0:1], v[0:1] op_sel:[0,0]
	v_pk_mov_b32 v[22:23], v[0:1], v[0:1] op_sel:[0,0]
	v_pk_mov_b32 v[24:25], v[0:1], v[0:1] op_sel:[0,0]
	v_pk_mov_b32 v[26:27], v[0:1], v[0:1] op_sel:[0,0]
	v_pk_mov_b32 v[28:29], v[0:1], v[0:1] op_sel:[0,0]
	v_pk_mov_b32 v[30:31], v[0:1], v[0:1] op_sel:[0,0]
	v_pk_mov_b32 v[32:33], v[0:1], v[0:1] op_sel:[0,0]
	v_pk_mov_b32 v[34:35], v[0:1], v[0:1] op_sel:[0,0]
	v_pk_mov_b32 v[36:37], v[0:1], v[0:1] op_sel:[0,0]
	v_pk_mov_b32 v[38:39], v[0:1], v[0:1] op_sel:[0,0]
	v_pk_mov_b32 v[40:41], v[0:1], v[0:1] op_sel:[0,0]
	v_pk_mov_b32 v[42:43], v[0:1], v[0:1] op_sel:[0,0]
	v_pk_mov_b32 v[44:45], v[0:1], v[0:1] op_sel:[0,0]
	v_pk_mov_b32 v[46:47], v[0:1], v[0:1] op_sel:[0,0]
	v_pk_mov_b32 v[48:49], v[0:1], v[0:1] op_sel:[0,0]
	v_pk_mov_b32 v[50:51], v[0:1], v[0:1] op_sel:[0,0]
	v_pk_mov_b32 v[52:53], v[0:1], v[0:1] op_sel:[0,0]
	v_pk_mov_b32 v[54:55], v[0:1], v[0:1] op_sel:[0,0]
	v_pk_mov_b32 v[56:57], v[0:1], v[0:1] op_sel:[0,0]
	v_pk_mov_b32 v[58:59], v[0:1], v[0:1] op_sel:[0,0]
	v_pk_mov_b32 v[60:61], v[0:1], v[0:1] op_sel:[0,0]
	v_pk_mov_b32 v[62:63], v[0:1], v[0:1] op_sel:[0,0]
	v_pk_mov_b32 v[64:65], v[0:1], v[0:1] op_sel:[0,0]
	v_pk_mov_b32 v[66:67], v[0:1], v[0:1] op_sel:[0,0]
	v_pk_mov_b32 v[68:69], v[0:1], v[0:1] op_sel:[0,0]
	v_pk_mov_b32 v[70:71], v[0:1], v[0:1] op_sel:[0,0]
	v_pk_mov_b32 v[72:73], v[0:1], v[0:1] op_sel:[0,0]
	v_pk_mov_b32 v[74:75], v[0:1], v[0:1] op_sel:[0,0]
	v_pk_mov_b32 v[76:77], v[0:1], v[0:1] op_sel:[0,0]
	v_pk_mov_b32 v[78:79], v[0:1], v[0:1] op_sel:[0,0]
	v_pk_mov_b32 v[80:81], v[0:1], v[0:1] op_sel:[0,0]
	v_pk_mov_b32 v[82:83], v[0:1], v[0:1] op_sel:[0,0]
	v_pk_mov_b32 v[84:85], v[0:1], v[0:1] op_sel:[0,0]
	v_pk_mov_b32 v[86:87], v[0:1], v[0:1] op_sel:[0,0]
	v_pk_mov_b32 v[88:89], v[0:1], v[0:1] op_sel:[0,0]
	v_pk_mov_b32 v[90:91], v[0:1], v[0:1] op_sel:[0,0]
	v_pk_mov_b32 v[92:93], v[0:1], v[0:1] op_sel:[0,0]
	v_pk_mov_b32 v[94:95], v[0:1], v[0:1] op_sel:[0,0]
	v_pk_mov_b32 v[96:97], v[0:1], v[0:1] op_sel:[0,0]
	v_pk_mov_b32 v[98:99], v[0:1], v[0:1] op_sel:[0,0]
	v_pk_mov_b32 v[100:101], v[0:1], v[0:1] op_sel:[0,0]
	v_pk_mov_b32 v[102:103], v[0:1], v[0:1] op_sel:[0,0]
	v_pk_mov_b32 v[104:105], v[0:1], v[0:1] op_sel:[0,0]
	v_pk_mov_b32 v[106:107], v[0:1], v[0:1] op_sel:[0,0]
	v_pk_mov_b32 v[108:109], v[0:1], v[0:1] op_sel:[0,0]
	v_pk_mov_b32 v[110:111], v[0:1], v[0:1] op_sel:[0,0]
	v_pk_mov_b32 v[112:113], v[0:1], v[0:1] op_sel:[0,0]
	v_pk_mov_b32 v[114:115], v[0:1], v[0:1] op_sel:[0,0]
	v_pk_mov_b32 v[116:117], v[0:1], v[0:1] op_sel:[0,0]
	v_pk_mov_b32 v[118:119], v[0:1], v[0:1] op_sel:[0,0]
	v_pk_mov_b32 v[120:121], v[0:1], v[0:1] op_sel:[0,0]
	v_pk_mov_b32 v[122:123], v[0:1], v[0:1] op_sel:[0,0]
	v_pk_mov_b32 v[124:125], v[0:1], v[0:1] op_sel:[0,0]
	v_pk_mov_b32 v[126:127], v[0:1], v[0:1] op_sel:[0,0]

.LBB0_1189:
	v_mov_b32_e32 v0, 0
	s_mov_b32 s25, 0
	s_mov_b64 s[36:37], -1
	s_mov_b64 s[38:39], 0
	v_mov_b32_e32 v1, v0
	v_pk_mov_b32 v[2:3], v[0:1], v[0:1] op_sel:[0,0]
	v_pk_mov_b32 v[4:5], v[0:1], v[0:1] op_sel:[0,0]
	v_pk_mov_b32 v[6:7], v[0:1], v[0:1] op_sel:[0,0]
	v_pk_mov_b32 v[8:9], v[0:1], v[0:1] op_sel:[0,0]
	v_pk_mov_b32 v[10:11], v[0:1], v[0:1] op_sel:[0,0]
	v_pk_mov_b32 v[12:13], v[0:1], v[0:1] op_sel:[0,0]
	v_pk_mov_b32 v[14:15], v[0:1], v[0:1] op_sel:[0,0]
	v_pk_mov_b32 v[16:17], v[0:1], v[0:1] op_sel:[0,0]
	v_pk_mov_b32 v[18:19], v[0:1], v[0:1] op_sel:[0,0]
	v_pk_mov_b32 v[20:21], v[0:1], v[0:1] op_sel:[0,0]
	v_pk_mov_b32 v[22:23], v[0:1], v[0:1] op_sel:[0,0]
	v_pk_mov_b32 v[24:25], v[0:1], v[0:1] op_sel:[0,0]
	v_pk_mov_b32 v[26:27], v[0:1], v[0:1] op_sel:[0,0]
	v_pk_mov_b32 v[28:29], v[0:1], v[0:1] op_sel:[0,0]
	v_pk_mov_b32 v[30:31], v[0:1], v[0:1] op_sel:[0,0]
	v_pk_mov_b32 v[32:33], v[0:1], v[0:1] op_sel:[0,0]
	v_pk_mov_b32 v[34:35], v[0:1], v[0:1] op_sel:[0,0]
	v_pk_mov_b32 v[36:37], v[0:1], v[0:1] op_sel:[0,0]
	v_pk_mov_b32 v[38:39], v[0:1], v[0:1] op_sel:[0,0]
	v_pk_mov_b32 v[40:41], v[0:1], v[0:1] op_sel:[0,0]
	v_pk_mov_b32 v[42:43], v[0:1], v[0:1] op_sel:[0,0]
	v_pk_mov_b32 v[44:45], v[0:1], v[0:1] op_sel:[0,0]
	v_pk_mov_b32 v[46:47], v[0:1], v[0:1] op_sel:[0,0]
	v_pk_mov_b32 v[48:49], v[0:1], v[0:1] op_sel:[0,0]
	v_pk_mov_b32 v[50:51], v[0:1], v[0:1] op_sel:[0,0]
	v_pk_mov_b32 v[52:53], v[0:1], v[0:1] op_sel:[0,0]
	v_pk_mov_b32 v[54:55], v[0:1], v[0:1] op_sel:[0,0]
	v_pk_mov_b32 v[56:57], v[0:1], v[0:1] op_sel:[0,0]
	v_pk_mov_b32 v[58:59], v[0:1], v[0:1] op_sel:[0,0]
	v_pk_mov_b32 v[60:61], v[0:1], v[0:1] op_sel:[0,0]
	v_pk_mov_b32 v[62:63], v[0:1], v[0:1] op_sel:[0,0]
	v_pk_mov_b32 v[64:65], v[0:1], v[0:1] op_sel:[0,0]
	v_pk_mov_b32 v[66:67], v[0:1], v[0:1] op_sel:[0,0]
	v_pk_mov_b32 v[68:69], v[0:1], v[0:1] op_sel:[0,0]
	v_pk_mov_b32 v[70:71], v[0:1], v[0:1] op_sel:[0,0]
	v_pk_mov_b32 v[72:73], v[0:1], v[0:1] op_sel:[0,0]
	v_pk_mov_b32 v[74:75], v[0:1], v[0:1] op_sel:[0,0]
	v_pk_mov_b32 v[76:77], v[0:1], v[0:1] op_sel:[0,0]
	v_pk_mov_b32 v[78:79], v[0:1], v[0:1] op_sel:[0,0]
	v_pk_mov_b32 v[80:81], v[0:1], v[0:1] op_sel:[0,0]
	v_pk_mov_b32 v[82:83], v[0:1], v[0:1] op_sel:[0,0]
	v_pk_mov_b32 v[84:85], v[0:1], v[0:1] op_sel:[0,0]
	v_pk_mov_b32 v[86:87], v[0:1], v[0:1] op_sel:[0,0]
	v_pk_mov_b32 v[88:89], v[0:1], v[0:1] op_sel:[0,0]
	v_pk_mov_b32 v[90:91], v[0:1], v[0:1] op_sel:[0,0]
	v_pk_mov_b32 v[92:93], v[0:1], v[0:1] op_sel:[0,0]
	v_pk_mov_b32 v[94:95], v[0:1], v[0:1] op_sel:[0,0]
	v_pk_mov_b32 v[96:97], v[0:1], v[0:1] op_sel:[0,0]
	v_pk_mov_b32 v[98:99], v[0:1], v[0:1] op_sel:[0,0]
	v_pk_mov_b32 v[100:101], v[0:1], v[0:1] op_sel:[0,0]
	v_pk_mov_b32 v[102:103], v[0:1], v[0:1] op_sel:[0,0]
	v_pk_mov_b32 v[104:105], v[0:1], v[0:1] op_sel:[0,0]
	v_pk_mov_b32 v[106:107], v[0:1], v[0:1] op_sel:[0,0]
	v_pk_mov_b32 v[108:109], v[0:1], v[0:1] op_sel:[0,0]
	v_pk_mov_b32 v[110:111], v[0:1], v[0:1] op_sel:[0,0]
	v_pk_mov_b32 v[112:113], v[0:1], v[0:1] op_sel:[0,0]
	v_pk_mov_b32 v[114:115], v[0:1], v[0:1] op_sel:[0,0]
	v_pk_mov_b32 v[116:117], v[0:1], v[0:1] op_sel:[0,0]
	v_pk_mov_b32 v[118:119], v[0:1], v[0:1] op_sel:[0,0]
	v_pk_mov_b32 v[120:121], v[0:1], v[0:1] op_sel:[0,0]
	v_pk_mov_b32 v[122:123], v[0:1], v[0:1] op_sel:[0,0]
	v_pk_mov_b32 v[124:125], v[0:1], v[0:1] op_sel:[0,0]
	v_pk_mov_b32 v[126:127], v[0:1], v[0:1] op_sel:[0,0]
